# in-projection epilogue: row rstd fetched once per wave (8 coalesced 16B loads, DPP pair-sum, wave-private LDS exchange) instead of 8 serialized gather round trips; attention row-max via v_max3 tree
# speedup vs baseline: 1.0374x; 1.0182x over previous
; DI unsigned pk2(float lo, float hi) { f32x2 v = {lo, hi}; return __builtin_bit_cast(unsigned, __builtin_convertvector(v, bf2_t)); }
;     DI void operator()(const f32x4 (&acc)[2][2][4][2], const pg8::Unit& u, int wr, int wc, int, int) const {
;     ...
;         float rs[2][4];
; #pragma unroll
;         for (int ai = 0; ai < 2; ++ai)
; #pragma unroll
;             for (int m = 0; m < 4; ++m) {
;                 const f32x4* sp = (const f32x4*)(ssq + (size_t)(row0 + ai * 128 + m * 16) * 16); const f32x4 q0 = sp[0], q1 = sp[1], q2 = sp[2], q3 = sp[3];
;                 rs[ai][m] = rsqrtf((((q0.x + q0.y) + (q0.z + q0.w)) + ((q1.x + q1.y) + (q1.z + q1.w)) + ((q2.x + q2.y) + (q2.z + q2.w)) + ((q3.x + q3.y) + (q3.z + q3.w))) * (1.0f / DM) + EPS);
;             }
; #pragma unroll
;         for (int ai = 0; ai < 2; ++ai)
; #pragma unroll
;             for (int m = 0; m < 4; ++m) {
;                 const int r = row0 + ai * 128 + m * 16;
;                 bf16_t* rowp = base + (size_t)r * ldc + col0;
; #pragma unroll
;                 for (int bj = 0; bj < 2; ++bj) {
;                     const f32x4 v0 = acc[ai][bj][m][0] * rs[ai][m], v1 = acc[ai][bj][m][1] * rs[ai][m];
;                     u32x4 w; w.x = pk2(v0[0], v0[1]); w.y = pk2(v0[2], v0[3]); w.z = pk2(v1[0], v1[1]); w.w = pk2(v1[2], v1[3]);
;                     *(u32x4*)(rowp + bj * 128) = w;
.LBB0_224:
	s_lshl_b32 s4, s4, 8
	s_add_i32 s4, s4, s86
	v_and_or_b32 v158, v130, 15, s4
	s_lshl_b32 s5, s4, 6
	v_lshlrev_b32_e32 v220, 5, v130
	v_add_u32_e32 v220, s5, v220
	global_load_dwordx4 v[222:225], v220, s[14:15]
	global_load_dwordx4 v[226:229], v220, s[14:15] offset:16
	global_load_dwordx4 v[230:233], v220, s[14:15] offset:2048
	global_load_dwordx4 v[234:237], v220, s[14:15] offset:2064
	v_add_u32_e32 v221, 0x2000, v220
	global_load_dwordx4 v[238:241], v221, s[14:15]
	global_load_dwordx4 v[242:245], v221, s[14:15] offset:16
	global_load_dwordx4 v[246:249], v221, s[14:15] offset:2048
	global_load_dwordx4 v[250:253], v221, s[14:15] offset:2064
	s_lshl_b32 s5, s33, 9
	v_lshrrev_b32_e32 v220, 1, v130
	v_lshlrev_b32_e32 v220, 2, v220
	v_add_u32_e32 v220, s5, v220
	v_add_u32_e32 v220, 0x20000, v220
	v_and_b32_e32 v221, 15, v130
	v_lshlrev_b32_e32 v221, 2, v221
	v_add_u32_e32 v221, s5, v221
	v_add_u32_e32 v221, 0x20000, v221
	s_waitcnt vmcnt(0)
	v_add_f32_e32 v222, v222, v223
	v_add_f32_e32 v224, v224, v225
	v_add_f32_e32 v226, v226, v227
	v_add_f32_e32 v228, v228, v229
	v_add_f32_e32 v222, v222, v224
	v_add_f32_e32 v226, v226, v228
	v_add_f32_e32 v222, v222, v226
	v_add_f32_e32 v230, v230, v231
	v_add_f32_e32 v232, v232, v233
	v_add_f32_e32 v234, v234, v235
	v_add_f32_e32 v236, v236, v237
	v_add_f32_e32 v230, v230, v232
	v_add_f32_e32 v234, v234, v236
	v_add_f32_e32 v230, v230, v234
	v_add_f32_e32 v238, v238, v239
	v_add_f32_e32 v240, v240, v241
	v_add_f32_e32 v242, v242, v243
	v_add_f32_e32 v244, v244, v245
	v_add_f32_e32 v238, v238, v240
	v_add_f32_e32 v242, v242, v244
	v_add_f32_e32 v238, v238, v242
	v_add_f32_e32 v246, v246, v247
	v_add_f32_e32 v248, v248, v249
	v_add_f32_e32 v250, v250, v251
	v_add_f32_e32 v252, v252, v253
	v_add_f32_e32 v246, v246, v248
	v_add_f32_e32 v250, v250, v252
	v_add_f32_e32 v246, v246, v250
	v_mov_b32_e32 v223, s90
	v_add_f32_dpp v222, v222, v222 quad_perm:[1,0,3,2] row_mask:0xf bank_mask:0xf
	v_add_f32_dpp v230, v230, v230 quad_perm:[1,0,3,2] row_mask:0xf bank_mask:0xf
	v_add_f32_dpp v238, v238, v238 quad_perm:[1,0,3,2] row_mask:0xf bank_mask:0xf
	v_add_f32_dpp v246, v246, v246 quad_perm:[1,0,3,2] row_mask:0xf bank_mask:0xf
	v_fma_f32 v222, v222, s88, v223
	v_fma_f32 v230, v230, s88, v223
	v_fma_f32 v238, v238, s88, v223
	v_fma_f32 v246, v246, s88, v223
	v_rsq_f32_e32 v222, v222
	v_rsq_f32_e32 v230, v230
	v_rsq_f32_e32 v238, v238
	v_rsq_f32_e32 v246, v246
	s_nop 1
	ds_write_b32 v220, v222
	ds_write_b32 v220, v230 offset:128
	ds_write_b32 v220, v238 offset:256
	ds_write_b32 v220, v246 offset:384
	s_waitcnt lgkmcnt(0)
	ds_read_b32 v222, v221 offset:0
	ds_read_b32 v224, v221 offset:64
	ds_read_b32 v226, v221 offset:128
	ds_read_b32 v228, v221 offset:192
	ds_read_b32 v230, v221 offset:256
	ds_read_b32 v232, v221 offset:320
	ds_read_b32 v234, v221 offset:384
	ds_read_b32 v236, v221 offset:448
	s_waitcnt lgkmcnt(0)
	v_ashrrev_i32_e32 v130, 1, v130
	v_ashrrev_i32_e32 v159, 31, v158
	v_and_b32_e32 v173, -8, v130
	s_nop 0
	v_add_u32_e32 v184, 0xa0, v158
	v_ashrrev_i32_e32 v185, 31, v184
	v_or_b32_e32 v160, 16, v158
	v_ashrrev_i32_e32 v161, 31, v160
	s_nop 0
	v_or_b32_e32 v168, 32, v158
	v_ashrrev_i32_e32 v169, 31, v168
	s_nop 0
	s_nop 0
	v_pk_mul_f32 v[128:129], v[128:129], v[222:223] op_sel_hi:[1,0]
	v_pk_mul_f32 v[126:127], v[126:127], v[222:223] op_sel_hi:[1,0]
	v_pk_mul_f32 v[116:117], v[116:117], v[222:223] op_sel_hi:[1,0]
	s_nop 0
	v_pk_mul_f32 v[114:115], v[114:115], v[222:223] op_sel_hi:[1,0]
	v_pk_mul_f32 v[112:113], v[112:113], v[224:225] op_sel_hi:[1,0]
	v_pk_mul_f32 v[110:111], v[110:111], v[224:225] op_sel_hi:[1,0]
	v_pk_mul_f32 v[100:101], v[100:101], v[224:225] op_sel_hi:[1,0]
	v_pk_mul_f32 v[98:99], v[98:99], v[224:225] op_sel_hi:[1,0]
	v_or_b32_e32 v170, 48, v158
	v_ashrrev_i32_e32 v171, 31, v170
	s_nop 0
	v_add_u32_e32 v176, 0x80, v158
	v_ashrrev_i32_e32 v177, 31, v176
	s_nop 0
	s_nop 0
	s_nop 0
	v_pk_mul_f32 v[96:97], v[96:97], v[226:227] op_sel_hi:[1,0]
	v_pk_mul_f32 v[94:95], v[94:95], v[226:227] op_sel_hi:[1,0]
	v_pk_mul_f32 v[84:85], v[84:85], v[226:227] op_sel_hi:[1,0]
	v_pk_mul_f32 v[82:83], v[82:83], v[226:227] op_sel_hi:[1,0]
	v_pk_mul_f32 v[80:81], v[80:81], v[228:229] op_sel_hi:[1,0]
	v_pk_mul_f32 v[78:79], v[78:79], v[228:229] op_sel_hi:[1,0]
	v_pk_mul_f32 v[72:73], v[72:73], v[228:229] op_sel_hi:[1,0]
	v_pk_mul_f32 v[70:71], v[70:71], v[228:229] op_sel_hi:[1,0]
	v_add_u32_e32 v178, 0x90, v158
	v_ashrrev_i32_e32 v179, 31, v178
	s_nop 0
	s_nop 0
	s_nop 0
	s_nop 0
	s_nop 0
	s_nop 0
	v_pk_mul_f32 v[64:65], v[64:65], v[230:231] op_sel_hi:[1,0]
	v_pk_mul_f32 v[62:63], v[62:63], v[230:231] op_sel_hi:[1,0]
	v_pk_mul_f32 v[52:53], v[52:53], v[230:231] op_sel_hi:[1,0]
	s_nop 0
	v_pk_mul_f32 v[50:51], v[50:51], v[230:231] op_sel_hi:[1,0]
	v_pk_mul_f32 v[48:49], v[48:49], v[232:233] op_sel_hi:[1,0]
	v_pk_mul_f32 v[46:47], v[46:47], v[232:233] op_sel_hi:[1,0]
	v_pk_mul_f32 v[36:37], v[36:37], v[232:233] op_sel_hi:[1,0]
	v_pk_mul_f32 v[34:35], v[34:35], v[232:233] op_sel_hi:[1,0]
	v_add_u32_e32 v186, 0xb0, v158
	v_ashrrev_i32_e32 v187, 31, v186
	s_nop 0
	v_pk_mul_f32 v[138:139], v[124:125], v[222:223] op_sel_hi:[1,0]
	v_pk_mul_f32 v[124:125], v[122:123], v[222:223] op_sel_hi:[1,0]
	v_cvt_pk_bf16_f32 v122, v126, v127
	v_cvt_pk_bf16_f32 v123, v128, v129
	v_cvt_pk_bf16_f32 v124, v124, v125
	v_cvt_pk_bf16_f32 v125, v138, v139
	s_add_i32 s4, s29, s87
	v_add_u32_e32 v134, s4, v173
	v_ashrrev_i32_e32 v135, 31, v134
	v_lshl_add_u64 v[134:135], v[134:135], 1, s[74:75]
	v_mad_i64_i32 v[136:137], s[4:5], s54, v158, 0
	v_lshl_add_u64 v[136:137], v[136:137], 1, v[134:135]
	flat_store_dwordx4 v[136:137], v[122:125]
; DI unsigned pk2(float lo, float hi) { f32x2 v = {lo, hi}; return __builtin_bit_cast(unsigned, __builtin_convertvector(v, bf2_t)); }
;     DI void operator()(const f32x4 (&acc)[2][2][4][2], const pg8::Unit& u, int wr, int wc, int, int) const {
;     ...
; #pragma unroll
;         for (int ai = 0; ai < 2; ++ai)
; #pragma unroll
;             for (int m = 0; m < 4; ++m) {
;                 const int r = row0 + ai * 128 + m * 16;
;                 bf16_t* rowp = base + (size_t)r * ldc + col0;
; #pragma unroll
;                 for (int bj = 0; bj < 2; ++bj) {
;                     const f32x4 v0 = acc[ai][bj][m][0] * rs[ai][m], v1 = acc[ai][bj][m][1] * rs[ai][m];
;                     u32x4 w; w.x = pk2(v0[0], v0[1]); w.y = pk2(v0[2], v0[3]); w.z = pk2(v1[0], v1[1]); w.w = pk2(v1[2], v1[3]);
;                     *(u32x4*)(rowp + bj * 128) = w;
;                 }
;             }
	s_nop 1
	v_pk_mul_f32 v[122:123], v[108:109], v[222:223] op_sel_hi:[1,0]
	v_pk_mul_f32 v[108:109], v[106:107], v[222:223] op_sel_hi:[1,0]
	v_cvt_pk_bf16_f32 v106, v114, v115
	v_cvt_pk_bf16_f32 v107, v116, v117
	v_cvt_pk_bf16_f32 v108, v108, v109
	v_cvt_pk_bf16_f32 v109, v122, v123
	flat_store_dwordx4 v[136:137], v[106:109] offset:256
	s_nop 1
	v_pk_mul_f32 v[32:33], v[32:33], v[234:235] op_sel_hi:[1,0]
	v_mad_i64_i32 v[106:107], s[4:5], s54, v160, 0
	v_lshl_add_u64 v[114:115], v[106:107], 1, v[134:135]
	v_pk_mul_f32 v[108:109], v[120:121], v[224:225] op_sel_hi:[1,0]
	v_pk_mul_f32 v[106:107], v[118:119], v[224:225] op_sel_hi:[1,0]
	v_pk_mul_f32 v[30:31], v[30:31], v[234:235] op_sel_hi:[1,0]
	v_cvt_pk_bf16_f32 v106, v106, v107
	v_cvt_pk_bf16_f32 v107, v108, v109
	v_cvt_pk_bf16_f32 v108, v110, v111
	v_cvt_pk_bf16_f32 v109, v112, v113
	flat_store_dwordx4 v[114:115], v[106:109]
	s_nop 1
	v_pk_mul_f32 v[20:21], v[20:21], v[234:235] op_sel_hi:[1,0]
	v_pk_mul_f32 v[18:19], v[18:19], v[234:235] op_sel_hi:[1,0]
	v_pk_mul_f32 v[106:107], v[92:93], v[224:225] op_sel_hi:[1,0]
	v_pk_mul_f32 v[92:93], v[90:91], v[224:225] op_sel_hi:[1,0]
	v_cvt_pk_bf16_f32 v90, v98, v99
	v_cvt_pk_bf16_f32 v91, v100, v101
	v_cvt_pk_bf16_f32 v92, v92, v93
	v_cvt_pk_bf16_f32 v93, v106, v107
	flat_store_dwordx4 v[114:115], v[90:93] offset:256
	s_nop 1
	v_mad_i64_i32 v[90:91], s[4:5], s54, v168, 0
	v_lshl_add_u64 v[98:99], v[90:91], 1, v[134:135]
	v_pk_mul_f32 v[92:93], v[104:105], v[226:227] op_sel_hi:[1,0]
	v_pk_mul_f32 v[90:91], v[102:103], v[226:227] op_sel_hi:[1,0]
	v_pk_mul_f32 v[16:17], v[16:17], v[236:237] op_sel_hi:[1,0]
	v_cvt_pk_bf16_f32 v90, v90, v91
	v_cvt_pk_bf16_f32 v91, v92, v93
	v_cvt_pk_bf16_f32 v92, v94, v95
	v_cvt_pk_bf16_f32 v93, v96, v97
	flat_store_dwordx4 v[98:99], v[90:93]
	s_nop 1
	v_pk_mul_f32 v[14:15], v[14:15], v[236:237] op_sel_hi:[1,0]
	v_pk_mul_f32 v[8:9], v[8:9], v[236:237] op_sel_hi:[1,0]
	v_pk_mul_f32 v[90:91], v[76:77], v[226:227] op_sel_hi:[1,0]
	v_pk_mul_f32 v[76:77], v[74:75], v[226:227] op_sel_hi:[1,0]
	v_cvt_pk_bf16_f32 v74, v82, v83
	v_cvt_pk_bf16_f32 v75, v84, v85
	v_cvt_pk_bf16_f32 v76, v76, v77
	v_cvt_pk_bf16_f32 v77, v90, v91
	flat_store_dwordx4 v[98:99], v[74:77] offset:256
	s_nop 1
	v_pk_mul_f32 v[6:7], v[6:7], v[236:237] op_sel_hi:[1,0]
	s_andn2_b64 vcc, exec, s[0:1]
	v_mad_i64_i32 v[74:75], s[4:5], s54, v170, 0
	v_lshl_add_u64 v[82:83], v[74:75], 1, v[134:135]
	v_pk_mul_f32 v[76:77], v[88:89], v[228:229] op_sel_hi:[1,0]
	v_pk_mul_f32 v[74:75], v[86:87], v[228:229] op_sel_hi:[1,0]
	s_nop 0
	v_cvt_pk_bf16_f32 v74, v74, v75
	v_cvt_pk_bf16_f32 v75, v76, v77
	v_cvt_pk_bf16_f32 v76, v78, v79
	v_cvt_pk_bf16_f32 v77, v80, v81
	flat_store_dwordx4 v[82:83], v[74:77]
	s_nop 1
	s_nop 1
	v_pk_mul_f32 v[74:75], v[68:69], v[228:229] op_sel_hi:[1,0]
	v_pk_mul_f32 v[68:69], v[66:67], v[228:229] op_sel_hi:[1,0]
	v_cvt_pk_bf16_f32 v66, v70, v71
	v_cvt_pk_bf16_f32 v67, v72, v73
	v_cvt_pk_bf16_f32 v68, v68, v69
	v_cvt_pk_bf16_f32 v69, v74, v75
	flat_store_dwordx4 v[82:83], v[66:69] offset:256
	s_nop 1
	s_nop 1
	v_mad_i64_i32 v[66:67], s[4:5], s54, v176, 0
	v_pk_mul_f32 v[68:69], v[60:61], v[230:231] op_sel_hi:[1,0]
	v_pk_mul_f32 v[60:61], v[58:59], v[230:231] op_sel_hi:[1,0]
	v_lshl_add_u64 v[66:67], v[66:67], 1, v[134:135]
	v_cvt_pk_bf16_f32 v58, v62, v63
	v_cvt_pk_bf16_f32 v59, v64, v65
	v_cvt_pk_bf16_f32 v60, v60, v61
	v_cvt_pk_bf16_f32 v61, v68, v69
	flat_store_dwordx4 v[66:67], v[58:61]
	s_nop 1
	s_nop 1
	v_pk_mul_f32 v[58:59], v[44:45], v[230:231] op_sel_hi:[1,0]
	v_pk_mul_f32 v[44:45], v[42:43], v[230:231] op_sel_hi:[1,0]
	v_cvt_pk_bf16_f32 v42, v50, v51
	v_cvt_pk_bf16_f32 v43, v52, v53
	v_cvt_pk_bf16_f32 v44, v44, v45
	v_cvt_pk_bf16_f32 v45, v58, v59
	flat_store_dwordx4 v[66:67], v[42:45] offset:256
	s_nop 1
	s_nop 1
	v_mad_i64_i32 v[42:43], s[4:5], s54, v178, 0
	v_lshl_add_u64 v[50:51], v[42:43], 1, v[134:135]
	v_pk_mul_f32 v[44:45], v[56:57], v[232:233] op_sel_hi:[1,0]
	v_pk_mul_f32 v[42:43], v[54:55], v[232:233] op_sel_hi:[1,0]
	s_nop 0
	v_cvt_pk_bf16_f32 v42, v42, v43
	v_cvt_pk_bf16_f32 v43, v44, v45
	v_cvt_pk_bf16_f32 v44, v46, v47
	v_cvt_pk_bf16_f32 v45, v48, v49
	flat_store_dwordx4 v[50:51], v[42:45]
	s_nop 1
	s_nop 1
	v_pk_mul_f32 v[42:43], v[28:29], v[232:233] op_sel_hi:[1,0]
	v_pk_mul_f32 v[28:29], v[26:27], v[232:233] op_sel_hi:[1,0]
	v_cvt_pk_bf16_f32 v26, v34, v35
	v_cvt_pk_bf16_f32 v27, v36, v37
	v_cvt_pk_bf16_f32 v28, v28, v29
	v_cvt_pk_bf16_f32 v29, v42, v43
	flat_store_dwordx4 v[50:51], v[26:29] offset:256
	s_nop 1
	s_nop 1
	v_mad_i64_i32 v[26:27], s[4:5], s54, v184, 0
	v_lshl_add_u64 v[34:35], v[26:27], 1, v[134:135]
	v_pk_mul_f32 v[28:29], v[40:41], v[234:235] op_sel_hi:[1,0]
	v_pk_mul_f32 v[26:27], v[38:39], v[234:235] op_sel_hi:[1,0]
	s_nop 0
	v_cvt_pk_bf16_f32 v26, v26, v27
	v_cvt_pk_bf16_f32 v27, v28, v29
	v_cvt_pk_bf16_f32 v28, v30, v31
	v_cvt_pk_bf16_f32 v29, v32, v33
	flat_store_dwordx4 v[34:35], v[26:29]
	s_nop 1
	s_nop 1
	v_pk_mul_f32 v[26:27], v[12:13], v[234:235] op_sel_hi:[1,0]
	v_pk_mul_f32 v[12:13], v[10:11], v[234:235] op_sel_hi:[1,0]
	v_cvt_pk_bf16_f32 v10, v18, v19
	v_cvt_pk_bf16_f32 v11, v20, v21
	v_cvt_pk_bf16_f32 v12, v12, v13
	v_cvt_pk_bf16_f32 v13, v26, v27
	flat_store_dwordx4 v[34:35], v[10:13] offset:256
	s_nop 1
	s_nop 1
	v_mad_i64_i32 v[10:11], s[4:5], s54, v186, 0
	v_lshl_add_u64 v[18:19], v[10:11], 1, v[134:135]
	v_pk_mul_f32 v[12:13], v[24:25], v[236:237] op_sel_hi:[1,0]
	v_pk_mul_f32 v[10:11], v[22:23], v[236:237] op_sel_hi:[1,0]
	s_mov_b64 s[4:5], -1
	v_cvt_pk_bf16_f32 v10, v10, v11
	v_cvt_pk_bf16_f32 v11, v12, v13
	v_cvt_pk_bf16_f32 v12, v14, v15
	v_cvt_pk_bf16_f32 v13, v16, v17
	flat_store_dwordx4 v[18:19], v[10:13]
	s_nop 1
	s_nop 1
	v_pk_mul_f32 v[10:11], v[4:5], v[236:237] op_sel_hi:[1,0]
	v_pk_mul_f32 v[4:5], v[2:3], v[236:237] op_sel_hi:[1,0]
	v_cvt_pk_bf16_f32 v2, v6, v7
	v_cvt_pk_bf16_f32 v3, v8, v9
	v_cvt_pk_bf16_f32 v4, v4, v5
	v_cvt_pk_bf16_f32 v5, v10, v11
	flat_store_dwordx4 v[18:19], v[2:5] offset:256
	s_nop 1
	s_cbranch_vccnz .LBB0_205
	s_andn2_b64 vcc, exec, s[12:13]
	s_cbranch_vccnz .LBB0_204
	s_barrier
	s_branch .LBB0_204

; DI void attn_unit(const Params& p, int b, int h, int qb, LAS unsigned char* lds, int tid, int lane, int wave) {
;     ...
;             float mx = fmaxf(fmaxf(fmaxf(s[0], s[1]), fmaxf(s[2], s[3])), fmaxf(fmaxf(s[4], s[5]), fmaxf(s[6], s[7])));
;             mx = fmaxf(mx, fmaxf(fmaxf(fmaxf(s[8], s[9]), fmaxf(s[10], s[11])), fmaxf(fmaxf(s[12], s[13]), fmaxf(s[14], s[15]))));
;             { const u32x2 sw = __builtin_amdgcn_permlane32_swap(__float_as_uint(mx), __float_as_uint(mx), false, false);
;               mx = fmaxf(__uint_as_float(sw.x), __uint_as_float(sw.y)); }
;             if (__builtin_amdgcn_ballot_w64(mx > mrow + 8.0f) != 0ull) {
;                 const float mnew = fmaxf(mrow, mx);
;                 const float alpha = (mnew == -INFINITY) ? 1.0f : __builtin_amdgcn_exp2f(mrow - mnew);
;                 mrow = mnew; lrow *= alpha;
; #pragma unroll
;                 for (int i = 0; i < 4; ++i)
; #pragma unroll
;                     for (int j = 0; j < 16; ++j) o[i][j] *= alpha;
;             }
.LBB0_432:
	s_nop 8
	v_max3_f32 v0, v66, v67, v68
	v_max3_f32 v194, v69, v70, v71
	v_max3_f32 v195, v72, v73, v74
	v_max3_f32 v196, v75, v76, v77
	v_max3_f32 v197, v78, v79, v80
	v_max3_f32 v0, v0, v194, v195
	v_max3_f32 v196, v196, v197, v81
	v_max_f32_e32 v0, v0, v196
	v_mov_b32_e32 v194, v0
	s_nop 1
	v_permlane32_swap_b32_e32 v0, v194
	v_max_f32_e32 v0, v0, v194
	v_add_f32_e32 v194, 0x41000000, v204
	v_cmp_gt_f32_e32 vcc, v0, v194
	s_cbranch_vccz .LBB0_427
	v_max_f32_e32 v0, v0, v0
	v_max_f32_e32 v194, v204, v204
	v_max_f32_e32 v194, v194, v0
	v_sub_f32_e32 v0, v204, v194
	v_exp_f32_e32 v0, v0
	v_cmp_neq_f32_e32 vcc, s58, v194
	v_mov_b32_e32 v204, v194
	s_nop 0
	v_cndmask_b32_e32 v0, 1.0, v0, vcc
	v_pk_mul_f32 v[64:65], v[64:65], v[0:1] op_sel_hi:[1,0]
	v_pk_mul_f32 v[62:63], v[62:63], v[0:1] op_sel_hi:[1,0]
	v_pk_mul_f32 v[60:61], v[60:61], v[0:1] op_sel_hi:[1,0]
	v_pk_mul_f32 v[58:59], v[58:59], v[0:1] op_sel_hi:[1,0]
	v_pk_mul_f32 v[56:57], v[56:57], v[0:1] op_sel_hi:[1,0]
	v_pk_mul_f32 v[54:55], v[54:55], v[0:1] op_sel_hi:[1,0]
	v_pk_mul_f32 v[52:53], v[52:53], v[0:1] op_sel_hi:[1,0]
	v_pk_mul_f32 v[50:51], v[50:51], v[0:1] op_sel_hi:[1,0]
	v_pk_mul_f32 v[48:49], v[48:49], v[0:1] op_sel_hi:[1,0]
	v_pk_mul_f32 v[46:47], v[46:47], v[0:1] op_sel_hi:[1,0]
	v_pk_mul_f32 v[44:45], v[44:45], v[0:1] op_sel_hi:[1,0]
	v_pk_mul_f32 v[42:43], v[42:43], v[0:1] op_sel_hi:[1,0]
	v_pk_mul_f32 v[40:41], v[40:41], v[0:1] op_sel_hi:[1,0]
	v_pk_mul_f32 v[38:39], v[38:39], v[0:1] op_sel_hi:[1,0]
	v_pk_mul_f32 v[36:37], v[36:37], v[0:1] op_sel_hi:[1,0]
	v_pk_mul_f32 v[34:35], v[34:35], v[0:1] op_sel_hi:[1,0]
	v_pk_mul_f32 v[32:33], v[32:33], v[0:1] op_sel_hi:[1,0]
	v_pk_mul_f32 v[30:31], v[30:31], v[0:1] op_sel_hi:[1,0]
	v_pk_mul_f32 v[28:29], v[28:29], v[0:1] op_sel_hi:[1,0]
	v_pk_mul_f32 v[26:27], v[26:27], v[0:1] op_sel_hi:[1,0]
	v_pk_mul_f32 v[24:25], v[24:25], v[0:1] op_sel_hi:[1,0]
	v_pk_mul_f32 v[22:23], v[22:23], v[0:1] op_sel_hi:[1,0]
	v_pk_mul_f32 v[20:21], v[20:21], v[0:1] op_sel_hi:[1,0]
	v_pk_mul_f32 v[18:19], v[18:19], v[0:1] op_sel_hi:[1,0]
	v_pk_mul_f32 v[16:17], v[16:17], v[0:1] op_sel_hi:[1,0]
	v_pk_mul_f32 v[14:15], v[14:15], v[0:1] op_sel_hi:[1,0]
	v_pk_mul_f32 v[12:13], v[12:13], v[0:1] op_sel_hi:[1,0]
	v_pk_mul_f32 v[10:11], v[10:11], v[0:1] op_sel_hi:[1,0]
	v_pk_mul_f32 v[8:9], v[8:9], v[0:1] op_sel_hi:[1,0]
	v_pk_mul_f32 v[6:7], v[6:7], v[0:1] op_sel_hi:[1,0]
	v_pk_mul_f32 v[4:5], v[4:5], v[0:1] op_sel_hi:[1,0]
	v_pk_mul_f32 v[2:3], v[2:3], v[0:1] op_sel_hi:[1,0]
	v_mul_f32_e32 v203, v203, v0
	s_branch .LBB0_427
